# P5 epilogue: the 1/sqrt row scale computed once per row (2 per lane) and shared by bpermute instead of 8 times per lane; plus first-iteration wait skip
# baseline (speedup 1.0000x reference)
.LBB5_639:
	v_mbcnt_lo_u32_b32 v248, -1, 0
	v_mbcnt_hi_u32_b32 v248, -1, v248
	v_and_b32_e32 v251, 15, v248
	v_lshlrev_b32_e32 v251, 2, v251
	v_add_u32_e32 v252, 64, v251
	v_add_u32_e32 v253, 0x80, v251
	v_add_u32_e32 v254, 0xc0, v251
	v_lshrrev_b32_e32 v248, 4, v248
	v_cmp_eq_u32_e64 s[84:85], 1, v248
	v_cmp_eq_u32_e64 s[86:87], 2, v248
	v_cmp_eq_u32_e64 s[88:89], 3, v248
	v_lshlrev_b32_e32 v248, 4, v248
	v_lshl_add_u32 v248, v180, 6, v248
	v_add_u32_e32 v249, 0x2000, v248
	global_load_dwordx4 v[144:147], v248, s[36:37]
	global_load_dwordx4 v[148:151], v248, s[36:37] offset:1024
	global_load_dwordx4 v[152:155], v248, s[36:37] offset:2048
	global_load_dwordx4 v[156:159], v248, s[36:37] offset:3072
	global_load_dwordx4 v[224:227], v249, s[36:37]
	global_load_dwordx4 v[228:231], v249, s[36:37] offset:1024
	global_load_dwordx4 v[232:235], v249, s[36:37] offset:2048
	global_load_dwordx4 v[236:239], v249, s[36:37] offset:3072
	s_waitcnt vmcnt(0)
	v_add_f32_e32 v144, v144, v145
	v_add_f32_e32 v146, v146, v147
	v_add_f32_e32 v148, v148, v149
	v_add_f32_e32 v150, v150, v151
	v_add_f32_e32 v152, v152, v153
	v_add_f32_e32 v154, v154, v155
	v_add_f32_e32 v156, v156, v157
	v_add_f32_e32 v158, v158, v159
	v_add_f32_e32 v224, v224, v225
	v_add_f32_e32 v226, v226, v227
	v_add_f32_e32 v228, v228, v229
	v_add_f32_e32 v230, v230, v231
	v_add_f32_e32 v232, v232, v233
	v_add_f32_e32 v234, v234, v235
	v_add_f32_e32 v236, v236, v237
	v_add_f32_e32 v238, v238, v239
	v_add_f32_e32 v144, v144, v146
	v_add_f32_e32 v148, v148, v150
	v_add_f32_e32 v152, v152, v154
	v_add_f32_e32 v156, v156, v158
	v_add_f32_e32 v224, v224, v226
	v_add_f32_e32 v228, v228, v230
	v_add_f32_e32 v232, v232, v234
	v_add_f32_e32 v236, v236, v238
	ds_bpermute_b32 v240, v251, v144
	ds_bpermute_b32 v145, v252, v144
	ds_bpermute_b32 v146, v253, v144
	ds_bpermute_b32 v147, v254, v144
	ds_bpermute_b32 v241, v251, v148
	ds_bpermute_b32 v149, v252, v148
	ds_bpermute_b32 v150, v253, v148
	ds_bpermute_b32 v151, v254, v148
	ds_bpermute_b32 v242, v251, v152
	ds_bpermute_b32 v153, v252, v152
	ds_bpermute_b32 v154, v253, v152
	ds_bpermute_b32 v155, v254, v152
	ds_bpermute_b32 v243, v251, v156
	ds_bpermute_b32 v157, v252, v156
	ds_bpermute_b32 v158, v253, v156
	ds_bpermute_b32 v159, v254, v156
	ds_bpermute_b32 v244, v251, v224
	ds_bpermute_b32 v225, v252, v224
	ds_bpermute_b32 v226, v253, v224
	ds_bpermute_b32 v227, v254, v224
	ds_bpermute_b32 v245, v251, v228
	ds_bpermute_b32 v229, v252, v228
	ds_bpermute_b32 v230, v253, v228
	ds_bpermute_b32 v231, v254, v228
	ds_bpermute_b32 v246, v251, v232
	ds_bpermute_b32 v233, v252, v232
	ds_bpermute_b32 v234, v253, v232
	ds_bpermute_b32 v235, v254, v232
	ds_bpermute_b32 v247, v251, v236
	ds_bpermute_b32 v237, v252, v236
	ds_bpermute_b32 v238, v253, v236
	ds_bpermute_b32 v239, v254, v236
	s_waitcnt lgkmcnt(0)
	v_add_f32_e32 v240, v240, v145
	v_add_f32_e32 v241, v241, v149
	v_add_f32_e32 v242, v242, v153
	v_add_f32_e32 v243, v243, v157
	v_add_f32_e32 v244, v244, v225
	v_add_f32_e32 v245, v245, v229
	v_add_f32_e32 v246, v246, v233
	v_add_f32_e32 v247, v247, v237
	v_add_f32_e32 v240, v240, v146
	v_add_f32_e32 v241, v241, v150
	v_add_f32_e32 v242, v242, v154
	v_add_f32_e32 v243, v243, v158
	v_add_f32_e32 v244, v244, v226
	v_add_f32_e32 v245, v245, v230
	v_add_f32_e32 v246, v246, v234
	v_add_f32_e32 v247, v247, v238
	v_add_f32_e32 v240, v240, v147
	v_add_f32_e32 v241, v241, v151
	v_add_f32_e32 v242, v242, v155
	v_add_f32_e32 v243, v243, v159
	v_add_f32_e32 v244, v244, v227
	v_add_f32_e32 v245, v245, v231
	v_add_f32_e32 v246, v246, v235
	v_add_f32_e32 v247, v247, v239
	v_mov_b32_e32 v236, v240
	v_cndmask_b32_e64 v236, v236, v241, s[84:85]
	v_cndmask_b32_e64 v236, v236, v242, s[86:87]
	v_cndmask_b32_e64 v236, v236, v243, s[88:89]
	v_mov_b32_e32 v237, v244
	v_cndmask_b32_e64 v237, v237, v245, s[84:85]
	v_cndmask_b32_e64 v237, v237, v246, s[86:87]
	v_cndmask_b32_e64 v237, v237, v247, s[88:89]
	v_fmamk_f32 v224, v236, 0x3a800000, v189
	v_mul_f32_e32 v225, 0x4f800000, v224
	v_cmp_gt_f32_e32 vcc, s82, v224
	s_nop 1
	v_cndmask_b32_e32 v224, v224, v225, vcc
	v_sqrt_f32_e32 v225, v224
	s_nop 0
	v_add_u32_e32 v226, -1, v225
	v_fma_f32 v227, -v226, v225, v224
	v_cmp_ge_f32_e64 s[94:95], 0, v227
	v_add_u32_e32 v227, 1, v225
	s_nop 0
	v_cndmask_b32_e64 v226, v225, v226, s[94:95]
	v_fma_f32 v225, -v227, v225, v224
	v_cmp_lt_f32_e64 s[94:95], 0, v225
	s_nop 1
	v_cndmask_b32_e64 v225, v226, v227, s[94:95]
	v_mul_f32_e32 v226, 0x37800000, v225
	v_cndmask_b32_e32 v225, v225, v226, vcc
	v_cmp_class_f32_e32 vcc, v224, v190
	s_nop 1
	v_cndmask_b32_e32 v224, v225, v224, vcc
	v_div_scale_f32 v225, s[94:95], v224, v224, 1.0
	v_rcp_f32_e32 v226, v225
	s_nop 0
	v_fma_f32 v227, -v225, v226, 1.0
	v_fmac_f32_e32 v226, v227, v226
	v_div_scale_f32 v227, vcc, 1.0, v224, 1.0
	v_mul_f32_e32 v228, v227, v226
	v_fma_f32 v229, -v225, v228, v227
	v_fmac_f32_e32 v228, v229, v226
	v_fma_f32 v225, -v225, v228, v227
	v_div_fmas_f32 v225, v225, v226, v228
	v_div_fixup_f32 v224, v225, v224, 1.0
	v_mul_f32_e32 v225, 0x3e38aa3b, v224
	v_cndmask_b32_e64 v226, v224, v225, s[6:7]
	v_fmamk_f32 v230, v237, 0x3a800000, v189
	v_mul_f32_e32 v231, 0x4f800000, v230
	v_cmp_gt_f32_e32 vcc, s82, v230
	s_nop 1
	v_cndmask_b32_e32 v230, v230, v231, vcc
	v_sqrt_f32_e32 v231, v230
	s_nop 0
	v_add_u32_e32 v232, -1, v231
	v_fma_f32 v233, -v232, v231, v230
	v_cmp_ge_f32_e64 s[94:95], 0, v233
	v_add_u32_e32 v233, 1, v231
	s_nop 0
	v_cndmask_b32_e64 v232, v231, v232, s[94:95]
	v_fma_f32 v231, -v233, v231, v230
	v_cmp_lt_f32_e64 s[94:95], 0, v231
	s_nop 1
	v_cndmask_b32_e64 v231, v232, v233, s[94:95]
	v_mul_f32_e32 v232, 0x37800000, v231
	v_cndmask_b32_e32 v231, v231, v232, vcc
	v_cmp_class_f32_e32 vcc, v230, v190
	s_nop 1
	v_cndmask_b32_e32 v230, v231, v230, vcc
	v_div_scale_f32 v231, s[94:95], v230, v230, 1.0
	v_rcp_f32_e32 v232, v231
	s_nop 0
	v_fma_f32 v233, -v231, v232, 1.0
	v_fmac_f32_e32 v232, v233, v232
	v_div_scale_f32 v233, vcc, 1.0, v230, 1.0
	v_mul_f32_e32 v234, v233, v232
	v_fma_f32 v235, -v231, v234, v233
	v_fmac_f32_e32 v234, v235, v232
	v_fma_f32 v231, -v231, v234, v233
	v_div_fmas_f32 v231, v231, v232, v234
	v_div_fixup_f32 v230, v231, v230, 1.0
	v_mul_f32_e32 v231, 0x3e38aa3b, v230
	v_cndmask_b32_e64 v232, v230, v231, s[6:7]
	ds_bpermute_b32 v240, v251, v226
	ds_bpermute_b32 v241, v252, v226
	ds_bpermute_b32 v242, v253, v226
	ds_bpermute_b32 v243, v254, v226
	ds_bpermute_b32 v244, v251, v232
	ds_bpermute_b32 v245, v252, v232
	ds_bpermute_b32 v246, v253, v232
	ds_bpermute_b32 v247, v254, v232
	s_waitcnt lgkmcnt(0)
	v_mov_b32_e32 v146, v240
	v_pk_mul_f32 v[142:143], v[142:143], v[146:147] op_sel_hi:[1,0]
	v_pk_mul_f32 v[140:141], v[140:141], v[146:147] op_sel_hi:[1,0]
	v_pk_mul_f32 v[138:139], v[138:139], v[146:147] op_sel_hi:[1,0]
	s_and_b64 vcc, exec, s[4:5]
	v_pk_mul_f32 v[148:149], v[136:137], v[146:147] op_sel_hi:[1,0]
	s_cbranch_vccnz .LBB5_643
	ds_bpermute_b32 v144, v185, v140
	ds_bpermute_b32 v136, v185, v148
	ds_bpermute_b32 v145, v185, v141
	ds_bpermute_b32 v137, v185, v149
	ds_bpermute_b32 v152, v185, v142
	ds_bpermute_b32 v151, v185, v138
	ds_bpermute_b32 v150, v185, v143
	ds_bpermute_b32 v147, v185, v139
	s_and_saveexec_b64 s[8:9], s[0:1]
	s_cbranch_execz .LBB5_642
	s_waitcnt lgkmcnt(2)
	v_mul_f32_e32 v151, v170, v151
	v_mul_f32_e32 v154, v42, v151
	s_waitcnt lgkmcnt(1)
	v_mul_f32_e32 v151, v170, v150
	v_mov_b32_e32 v156, v143
	v_mov_b32_e32 v157, v47
	v_mov_b32_e32 v150, v39
	v_pk_mul_f32 v[140:141], v[140:141], v[36:37]
	v_pk_mul_f32 v[144:145], v[170:171], v[144:145]
	v_pk_mul_f32 v[150:151], v[156:157], v[150:151]
	v_pk_fma_f32 v[140:141], v[44:45], v[144:145], v[140:141]
	v_mov_b32_e32 v143, v150
	v_mov_b32_e32 v153, v151
	s_waitcnt lgkmcnt(0)
	v_mul_f32_e32 v145, v170, v147
	v_mov_b32_e32 v150, v139
	v_mov_b32_e32 v151, v43
	v_mov_b32_e32 v144, v35
	v_mul_f32_e32 v152, v170, v152
	v_pk_mul_f32 v[144:145], v[150:151], v[144:145]
	v_pk_mul_f32 v[148:149], v[148:149], v[32:33]
	v_pk_mul_f32 v[136:137], v[170:171], v[136:137]
	v_mul_f32_e32 v142, v142, v38
	v_mul_f32_e32 v152, v46, v152
	v_mul_f32_e32 v138, v138, v34
	v_mov_b32_e32 v139, v144
	v_mov_b32_e32 v155, v145
	v_pk_add_f32 v[142:143], v[142:143], v[152:153]
	v_pk_fma_f32 v[148:149], v[40:41], v[136:137], v[148:149]
	v_pk_add_f32 v[138:139], v[138:139], v[154:155]

.LBB5_653:
	v_mov_b32_e32 v128, v241
	v_pk_mul_f32 v[126:127], v[126:127], v[128:129] op_sel_hi:[1,0]
	v_pk_mul_f32 v[124:125], v[124:125], v[128:129] op_sel_hi:[1,0]
	v_pk_mul_f32 v[122:123], v[122:123], v[128:129] op_sel_hi:[1,0]
	s_and_b64 vcc, exec, s[4:5]
	v_pk_mul_f32 v[130:131], v[120:121], v[128:129] op_sel_hi:[1,0]
	s_cbranch_vccnz .LBB5_657
	ds_bpermute_b32 v132, v185, v124
	ds_bpermute_b32 v120, v185, v130
	ds_bpermute_b32 v133, v185, v125
	ds_bpermute_b32 v121, v185, v131
	ds_bpermute_b32 v136, v185, v126
	ds_bpermute_b32 v135, v185, v122
	ds_bpermute_b32 v134, v185, v127
	ds_bpermute_b32 v129, v185, v123
	s_and_saveexec_b64 s[12:13], s[0:1]
	s_cbranch_execz .LBB5_656
	s_waitcnt lgkmcnt(2)
	v_mul_f32_e32 v135, v170, v135
	v_mul_f32_e32 v138, v202, v135
	s_waitcnt lgkmcnt(1)
	v_mul_f32_e32 v135, v170, v134
	v_mov_b32_e32 v140, v127
	v_mov_b32_e32 v141, v207
	v_mov_b32_e32 v134, v199
	v_pk_mul_f32 v[124:125], v[124:125], v[196:197]
	v_pk_mul_f32 v[132:133], v[170:171], v[132:133]
	v_pk_mul_f32 v[134:135], v[140:141], v[134:135]
	v_pk_fma_f32 v[124:125], v[204:205], v[132:133], v[124:125]
	v_mov_b32_e32 v127, v134
	v_mov_b32_e32 v137, v135
	s_waitcnt lgkmcnt(0)
	v_mul_f32_e32 v133, v170, v129
	v_mov_b32_e32 v134, v123
	v_mov_b32_e32 v135, v203
	v_mov_b32_e32 v132, v195
	v_mul_f32_e32 v136, v170, v136
	v_pk_mul_f32 v[132:133], v[134:135], v[132:133]
	v_pk_mul_f32 v[130:131], v[130:131], v[192:193]
	v_pk_mul_f32 v[120:121], v[170:171], v[120:121]
	v_mul_f32_e32 v126, v126, v198
	v_mul_f32_e32 v136, v206, v136
	v_mul_f32_e32 v122, v122, v194
	v_mov_b32_e32 v123, v132
	v_mov_b32_e32 v139, v133
	v_pk_add_f32 v[126:127], v[126:127], v[136:137]
	v_pk_fma_f32 v[130:131], v[200:201], v[120:121], v[130:131]
	v_pk_add_f32 v[122:123], v[122:123], v[138:139]

.LBB5_667:
	v_mov_b32_e32 v112, v242
	v_pk_mul_f32 v[110:111], v[110:111], v[112:113] op_sel_hi:[1,0]
	v_pk_mul_f32 v[108:109], v[108:109], v[112:113] op_sel_hi:[1,0]
	v_pk_mul_f32 v[106:107], v[106:107], v[112:113] op_sel_hi:[1,0]
	s_and_b64 vcc, exec, s[4:5]
	v_pk_mul_f32 v[114:115], v[104:105], v[112:113] op_sel_hi:[1,0]
	s_cbranch_vccnz .LBB5_671
	ds_bpermute_b32 v116, v185, v108
	ds_bpermute_b32 v104, v185, v114
	ds_bpermute_b32 v117, v185, v109
	ds_bpermute_b32 v105, v185, v115
	ds_bpermute_b32 v120, v185, v110
	ds_bpermute_b32 v119, v185, v106
	ds_bpermute_b32 v118, v185, v111
	ds_bpermute_b32 v113, v185, v107
	s_and_saveexec_b64 s[12:13], s[0:1]
	s_cbranch_execz .LBB5_670
	s_waitcnt lgkmcnt(2)
	v_mul_f32_e32 v119, v170, v119
	v_mul_f32_e32 v122, v218, v119
	s_waitcnt lgkmcnt(1)
	v_mul_f32_e32 v119, v170, v118
	v_mov_b32_e32 v124, v111
	v_mov_b32_e32 v125, v223
	v_mov_b32_e32 v118, v215
	v_pk_mul_f32 v[108:109], v[108:109], v[212:213]
	v_pk_mul_f32 v[116:117], v[170:171], v[116:117]
	v_pk_mul_f32 v[118:119], v[124:125], v[118:119]
	v_pk_fma_f32 v[108:109], v[220:221], v[116:117], v[108:109]
	v_mov_b32_e32 v111, v118
	v_mov_b32_e32 v121, v119
	s_waitcnt lgkmcnt(0)
	v_mul_f32_e32 v117, v170, v113
	v_mov_b32_e32 v118, v107
	v_mov_b32_e32 v119, v219
	v_mov_b32_e32 v116, v211
	v_mul_f32_e32 v120, v170, v120
	v_pk_mul_f32 v[116:117], v[118:119], v[116:117]
	v_pk_mul_f32 v[114:115], v[114:115], v[208:209]
	v_pk_mul_f32 v[104:105], v[170:171], v[104:105]
	v_mul_f32_e32 v110, v110, v214
	v_mul_f32_e32 v120, v222, v120
	v_mul_f32_e32 v106, v106, v210
	v_mov_b32_e32 v107, v116
	v_mov_b32_e32 v123, v117
	v_pk_add_f32 v[110:111], v[110:111], v[120:121]
	v_pk_fma_f32 v[114:115], v[216:217], v[104:105], v[114:115]
	v_pk_add_f32 v[106:107], v[106:107], v[122:123]

.LBB5_681:
	v_mov_b32_e32 v96, v243
	v_pk_mul_f32 v[94:95], v[94:95], v[96:97] op_sel_hi:[1,0]
	v_pk_mul_f32 v[92:93], v[92:93], v[96:97] op_sel_hi:[1,0]
	v_pk_mul_f32 v[90:91], v[90:91], v[96:97] op_sel_hi:[1,0]
	s_and_b64 vcc, exec, s[4:5]
	v_pk_mul_f32 v[98:99], v[88:89], v[96:97] op_sel_hi:[1,0]
	s_cbranch_vccnz .LBB5_685
	ds_bpermute_b32 v100, v185, v92
	ds_bpermute_b32 v88, v185, v98
	ds_bpermute_b32 v101, v185, v93
	ds_bpermute_b32 v89, v185, v99
	ds_bpermute_b32 v104, v185, v94
	ds_bpermute_b32 v103, v185, v90
	ds_bpermute_b32 v102, v185, v95
	ds_bpermute_b32 v97, v185, v91
	s_and_saveexec_b64 s[12:13], s[0:1]
	s_cbranch_execz .LBB5_684
	s_waitcnt lgkmcnt(2)
	v_mul_f32_e32 v103, v170, v103
	v_mul_f32_e32 v106, v42, v103
	s_waitcnt lgkmcnt(1)
	v_mul_f32_e32 v103, v170, v102
	v_mov_b32_e32 v108, v95
	v_mov_b32_e32 v109, v47
	v_mov_b32_e32 v102, v39
	v_pk_mul_f32 v[92:93], v[92:93], v[36:37]
	v_pk_mul_f32 v[100:101], v[170:171], v[100:101]
	v_pk_mul_f32 v[102:103], v[108:109], v[102:103]
	v_pk_fma_f32 v[92:93], v[44:45], v[100:101], v[92:93]
	v_mov_b32_e32 v95, v102
	v_mov_b32_e32 v105, v103
	s_waitcnt lgkmcnt(0)
	v_mul_f32_e32 v101, v170, v97
	v_mov_b32_e32 v102, v91
	v_mov_b32_e32 v103, v43
	v_mov_b32_e32 v100, v35
	v_mul_f32_e32 v104, v170, v104
	v_pk_mul_f32 v[100:101], v[102:103], v[100:101]
	v_pk_mul_f32 v[98:99], v[98:99], v[32:33]
	v_pk_mul_f32 v[88:89], v[170:171], v[88:89]
	v_mul_f32_e32 v94, v94, v38
	v_mul_f32_e32 v104, v46, v104
	v_mul_f32_e32 v90, v90, v34
	v_mov_b32_e32 v91, v100
	v_mov_b32_e32 v107, v101
	v_pk_add_f32 v[94:95], v[94:95], v[104:105]
	v_pk_fma_f32 v[98:99], v[40:41], v[88:89], v[98:99]
	v_pk_add_f32 v[90:91], v[90:91], v[106:107]

.LBB5_695:
	v_mov_b32_e32 v80, v244
	v_pk_mul_f32 v[78:79], v[78:79], v[80:81] op_sel_hi:[1,0]
	v_pk_mul_f32 v[76:77], v[76:77], v[80:81] op_sel_hi:[1,0]
	v_pk_mul_f32 v[74:75], v[74:75], v[80:81] op_sel_hi:[1,0]
	s_and_b64 vcc, exec, s[4:5]
	v_pk_mul_f32 v[82:83], v[72:73], v[80:81] op_sel_hi:[1,0]
	s_cbranch_vccnz .LBB5_699
	ds_bpermute_b32 v84, v185, v76
	ds_bpermute_b32 v72, v185, v82
	ds_bpermute_b32 v85, v185, v77
	ds_bpermute_b32 v73, v185, v83
	ds_bpermute_b32 v88, v185, v78
	ds_bpermute_b32 v87, v185, v74
	ds_bpermute_b32 v86, v185, v79
	ds_bpermute_b32 v81, v185, v75
	s_and_saveexec_b64 s[12:13], s[0:1]
	s_cbranch_execz .LBB5_698
	s_waitcnt lgkmcnt(2)
	v_mul_f32_e32 v87, v170, v87
	v_mul_f32_e32 v90, v202, v87
	s_waitcnt lgkmcnt(1)
	v_mul_f32_e32 v87, v170, v86
	v_mov_b32_e32 v92, v79
	v_mov_b32_e32 v93, v207
	v_mov_b32_e32 v86, v199
	v_pk_mul_f32 v[76:77], v[76:77], v[196:197]
	v_pk_mul_f32 v[84:85], v[170:171], v[84:85]
	v_pk_mul_f32 v[86:87], v[92:93], v[86:87]
	v_pk_fma_f32 v[76:77], v[204:205], v[84:85], v[76:77]
	v_mov_b32_e32 v79, v86
	v_mov_b32_e32 v89, v87
	s_waitcnt lgkmcnt(0)
	v_mul_f32_e32 v85, v170, v81
	v_mov_b32_e32 v86, v75
	v_mov_b32_e32 v87, v203
	v_mov_b32_e32 v84, v195
	v_mul_f32_e32 v88, v170, v88
	v_pk_mul_f32 v[84:85], v[86:87], v[84:85]
	v_pk_mul_f32 v[82:83], v[82:83], v[192:193]
	v_pk_mul_f32 v[72:73], v[170:171], v[72:73]
	v_mul_f32_e32 v78, v78, v198
	v_mul_f32_e32 v88, v206, v88
	v_mul_f32_e32 v74, v74, v194
	v_mov_b32_e32 v75, v84
	v_mov_b32_e32 v91, v85
	v_pk_add_f32 v[78:79], v[78:79], v[88:89]
	v_pk_fma_f32 v[82:83], v[200:201], v[72:73], v[82:83]
	v_pk_add_f32 v[74:75], v[74:75], v[90:91]

.LBB5_709:
	v_mov_b32_e32 v64, v245
	v_pk_mul_f32 v[62:63], v[62:63], v[64:65] op_sel_hi:[1,0]
	v_pk_mul_f32 v[60:61], v[60:61], v[64:65] op_sel_hi:[1,0]
	v_pk_mul_f32 v[58:59], v[58:59], v[64:65] op_sel_hi:[1,0]
	s_and_b64 vcc, exec, s[4:5]
	v_pk_mul_f32 v[66:67], v[56:57], v[64:65] op_sel_hi:[1,0]
	s_cbranch_vccnz .LBB5_713
	ds_bpermute_b32 v68, v185, v60
	ds_bpermute_b32 v56, v185, v66
	ds_bpermute_b32 v69, v185, v61
	ds_bpermute_b32 v57, v185, v67
	ds_bpermute_b32 v72, v185, v62
	ds_bpermute_b32 v71, v185, v58
	ds_bpermute_b32 v70, v185, v63
	ds_bpermute_b32 v65, v185, v59
	s_and_saveexec_b64 s[12:13], s[0:1]
	s_cbranch_execz .LBB5_712
	s_waitcnt lgkmcnt(2)
	v_mul_f32_e32 v71, v170, v71
	v_mul_f32_e32 v74, v218, v71
	s_waitcnt lgkmcnt(1)
	v_mul_f32_e32 v71, v170, v70
	v_mov_b32_e32 v76, v63
	v_mov_b32_e32 v77, v223
	v_mov_b32_e32 v70, v215
	v_pk_mul_f32 v[60:61], v[60:61], v[212:213]
	v_pk_mul_f32 v[68:69], v[170:171], v[68:69]
	v_pk_mul_f32 v[70:71], v[76:77], v[70:71]
	v_pk_fma_f32 v[60:61], v[220:221], v[68:69], v[60:61]
	v_mov_b32_e32 v63, v70
	v_mov_b32_e32 v73, v71
	s_waitcnt lgkmcnt(0)
	v_mul_f32_e32 v69, v170, v65
	v_mov_b32_e32 v70, v59
	v_mov_b32_e32 v71, v219
	v_mov_b32_e32 v68, v211
	v_mul_f32_e32 v72, v170, v72
	v_pk_mul_f32 v[68:69], v[70:71], v[68:69]
	v_pk_mul_f32 v[66:67], v[66:67], v[208:209]
	v_pk_mul_f32 v[56:57], v[170:171], v[56:57]
	v_mul_f32_e32 v62, v62, v214
	v_mul_f32_e32 v72, v222, v72
	v_mul_f32_e32 v58, v58, v210
	v_mov_b32_e32 v59, v68
	v_mov_b32_e32 v75, v69
	v_pk_add_f32 v[62:63], v[62:63], v[72:73]
	v_pk_fma_f32 v[66:67], v[216:217], v[56:57], v[66:67]
	v_pk_add_f32 v[58:59], v[58:59], v[74:75]

.LBB5_723:
	v_mov_b32_e32 v48, v246
	v_pk_mul_f32 v[30:31], v[30:31], v[48:49] op_sel_hi:[1,0]
	v_pk_mul_f32 v[28:29], v[28:29], v[48:49] op_sel_hi:[1,0]
	v_pk_mul_f32 v[26:27], v[26:27], v[48:49] op_sel_hi:[1,0]
	s_and_b64 vcc, exec, s[4:5]
	v_pk_mul_f32 v[50:51], v[24:25], v[48:49] op_sel_hi:[1,0]
	s_cbranch_vccnz .LBB5_727
	ds_bpermute_b32 v52, v185, v28
	ds_bpermute_b32 v24, v185, v50
	ds_bpermute_b32 v53, v185, v29
	ds_bpermute_b32 v25, v185, v51
	ds_bpermute_b32 v56, v185, v30
	ds_bpermute_b32 v55, v185, v26
	ds_bpermute_b32 v54, v185, v31
	ds_bpermute_b32 v49, v185, v27
	s_and_saveexec_b64 s[12:13], s[0:1]
	s_cbranch_execz .LBB5_726
	s_waitcnt lgkmcnt(2)
	v_mul_f32_e32 v55, v170, v55
	v_mul_f32_e32 v58, v42, v55
	s_waitcnt lgkmcnt(1)
	v_mul_f32_e32 v55, v170, v54
	v_mov_b32_e32 v60, v31
	v_mov_b32_e32 v61, v47
	v_mov_b32_e32 v54, v39
	v_pk_mul_f32 v[28:29], v[28:29], v[36:37]
	v_pk_mul_f32 v[52:53], v[170:171], v[52:53]
	v_pk_mul_f32 v[54:55], v[60:61], v[54:55]
	v_pk_fma_f32 v[28:29], v[44:45], v[52:53], v[28:29]
	v_mov_b32_e32 v31, v54
	v_mov_b32_e32 v57, v55
	s_waitcnt lgkmcnt(0)
	v_mul_f32_e32 v53, v170, v49
	v_mov_b32_e32 v54, v27
	v_mov_b32_e32 v55, v43
	v_mov_b32_e32 v52, v35
	v_mul_f32_e32 v56, v170, v56
	v_pk_mul_f32 v[52:53], v[54:55], v[52:53]
	v_pk_mul_f32 v[50:51], v[50:51], v[32:33]
	v_pk_mul_f32 v[24:25], v[170:171], v[24:25]
	v_mul_f32_e32 v30, v30, v38
	v_mul_f32_e32 v56, v46, v56
	v_mul_f32_e32 v26, v26, v34
	v_mov_b32_e32 v27, v52
	v_mov_b32_e32 v59, v53
	v_pk_add_f32 v[30:31], v[30:31], v[56:57]
	v_pk_fma_f32 v[50:51], v[40:41], v[24:25], v[50:51]
	v_pk_add_f32 v[26:27], v[26:27], v[58:59]

.LBB5_737:
	v_mov_b32_e32 v16, v247
	v_pk_mul_f32 v[14:15], v[14:15], v[16:17] op_sel_hi:[1,0]
	v_pk_mul_f32 v[12:13], v[12:13], v[16:17] op_sel_hi:[1,0]
	v_pk_mul_f32 v[10:11], v[10:11], v[16:17] op_sel_hi:[1,0]
	s_and_b64 vcc, exec, s[4:5]
	v_pk_mul_f32 v[18:19], v[8:9], v[16:17] op_sel_hi:[1,0]
	s_cbranch_vccnz .LBB5_741
	ds_bpermute_b32 v20, v185, v12
	ds_bpermute_b32 v8, v185, v18
	ds_bpermute_b32 v21, v185, v13
	ds_bpermute_b32 v9, v185, v19
	ds_bpermute_b32 v24, v185, v14
	ds_bpermute_b32 v23, v185, v10
	ds_bpermute_b32 v22, v185, v15
	ds_bpermute_b32 v17, v185, v11
	s_and_saveexec_b64 s[6:7], s[0:1]
	s_cbranch_execz .LBB5_740
	s_waitcnt lgkmcnt(2)
	v_mul_f32_e32 v23, v170, v23
	v_mul_f32_e32 v26, v202, v23
	s_waitcnt lgkmcnt(1)
	v_mul_f32_e32 v23, v170, v22
	v_mov_b32_e32 v28, v15
	v_mov_b32_e32 v29, v207
	v_mov_b32_e32 v22, v199
	v_pk_mul_f32 v[12:13], v[12:13], v[196:197]
	v_pk_mul_f32 v[20:21], v[170:171], v[20:21]
	v_pk_mul_f32 v[22:23], v[28:29], v[22:23]
	v_pk_fma_f32 v[12:13], v[204:205], v[20:21], v[12:13]
	v_mov_b32_e32 v15, v22
	v_mov_b32_e32 v25, v23
	s_waitcnt lgkmcnt(0)
	v_mul_f32_e32 v21, v170, v17
	v_mov_b32_e32 v22, v11
	v_mov_b32_e32 v23, v203
	v_mov_b32_e32 v20, v195
	v_mul_f32_e32 v24, v170, v24
	v_pk_mul_f32 v[20:21], v[22:23], v[20:21]
	v_pk_mul_f32 v[18:19], v[18:19], v[192:193]
	v_pk_mul_f32 v[8:9], v[170:171], v[8:9]
	v_mul_f32_e32 v14, v14, v198
	v_mul_f32_e32 v24, v206, v24
	v_mul_f32_e32 v10, v10, v194
	v_mov_b32_e32 v11, v20
	v_mov_b32_e32 v27, v21
	v_pk_add_f32 v[14:15], v[14:15], v[24:25]
	v_pk_fma_f32 v[18:19], v[200:201], v[8:9], v[18:19]
	v_pk_add_f32 v[10:11], v[10:11], v[26:27]

.LBB5_753:
	s_nop 0
	s_nop 0
	s_nop 0
	s_nop 0
	s_nop 0
	s_nop 0
	s_nop 0
	s_nop 0
	s_nop 0
	s_nop 0
	s_cmp_gt_i32 s75, 6
	s_cselect_b64 s[0:1], -1, 0
	s_and_b64 s[4:5], s[14:15], s[0:1]
	s_and_b64 vcc, exec, s[4:5]
	s_cbranch_vccz .LBB5_803
	v_mbcnt_lo_u32_b32 v0, -1, 0
	v_readlane_b32 s3, v250, 0
	v_mbcnt_hi_u32_b32 v0, -1, v0
	s_waitcnt vmcnt(0)
	s_andn2_b32 s3, s3, 63
	v_sub_u32_e32 v0, 0, v0
	v_cmp_eq_u32_e32 vcc, s3, v0
	s_waitcnt lgkmcnt(0)
	s_barrier
	s_and_saveexec_b64 s[4:5], vcc
	s_cbranch_execz .LBB5_802
	v_mov_b32_e32 v0, s61
	s_waitcnt vmcnt(0) expcnt(0) lgkmcnt(0)
	ds_read_b32 v2, v0
	ds_read_b32 v0, v0 offset:4
	s_waitcnt lgkmcnt(1)
	v_cmp_ne_u32_e32 vcc, 0, v2
	s_cbranch_vccnz .LBB5_770
	v_readlane_b32 s6, v250, 1
	v_readlane_b32 s7, v250, 2
	s_load_dwordx2 s[10:11], s[6:7], 0x4
	s_add_u32 s6, s72, 0x4200
	s_addc_u32 s7, s73, 0
	s_add_u32 s8, s72, 0x4400
	s_addc_u32 s9, s73, 0
	s_waitcnt lgkmcnt(0)
	s_mul_i32 s3, s10, s90
	s_add_u32 s10, s72, 0x4500
	s_mul_i32 s3, s3, s11
	s_addc_u32 s11, s73, 0
	s_add_u32 s12, s72, 0x4600
	s_addc_u32 s13, s73, 0
	s_add_u32 s14, s72, 0x4700
	s_addc_u32 s15, s73, 0
	s_add_u32 s16, s72, 0x4800
	s_addc_u32 s17, s73, 0
	s_add_u32 s18, s72, 0x4900
	s_addc_u32 s19, s73, 0
	s_add_u32 s20, s72, 0x4a00
	s_addc_u32 s21, s73, 0
	s_add_u32 s22, s72, 0x4b00
	s_addc_u32 s23, s73, 0
	s_add_u32 s26, s72, 0x4c00
	s_addc_u32 s27, s73, 0
	s_add_u32 s36, s72, 0x4d00
	s_addc_u32 s37, s73, 0
	s_add_u32 s38, s72, 0x4e00
	s_addc_u32 s39, s73, 0
	s_add_u32 s40, s72, 0x4f00
	s_addc_u32 s41, s73, 0
	s_add_u32 s42, s72, 0x5000
	s_addc_u32 s43, s73, 0
	s_add_u32 s44, s72, 0x5100
	s_addc_u32 s45, s73, 0
	s_add_u32 s46, s72, 0x5200
	s_addc_u32 s47, s73, 0
	s_add_u32 s48, s72, 0x5300
	s_addc_u32 s49, s73, 0
	s_mov_b32 s24, 1
	v_mov_b32_e32 v16, 0
	s_branch .LBB5_758
